# nsa accum-epilogue prefetch, bias loop rolling loads, dead rope table removed, dead pad keeps GEMM loop alignment
# baseline (speedup 1.0000x reference)
.LBB0_171:
	s_or_b64 exec, exec, s[6:7]
	v_readlane_b32 s79, v254, 7
	s_mov_b32 s2, s79
	s_mov_b32 s3, 0x8000
	v_lshl_add_u32 v2, s2, 9, v82
	v_cmp_gt_i32_e32 vcc, s3, v2
	s_waitcnt lgkmcnt(0)
	s_and_saveexec_b64 s[14:15], vcc
	s_branch .LBB0_183
	s_nop 0
	s_nop 0
	s_nop 0
	s_nop 0
	s_nop 0
	s_nop 0
	s_nop 0
	s_nop 0
	s_nop 0
	s_nop 0
	s_nop 0
	s_nop 0
	s_nop 0
	s_nop 0
	s_nop 0
	s_nop 0
	s_nop 0
	s_nop 0
	s_nop 0
	s_nop 0
	s_nop 0
	s_nop 0
	s_nop 0
	s_nop 0
	s_nop 0
	s_nop 0
	s_nop 0

.LBB0_186:
	global_load_dwordx4 v[136:139], v[6:7], off offset:16
	global_load_dwordx4 v[132:135], v[6:7], off
	v_add_co_u32_e32 v250, vcc, 0xfffff000, v4
	s_nop 1
	v_addc_co_u32_e32 v251, vcc, -1, v5, vcc
	global_load_dword v140, v[250:251], off offset:-3072
	global_load_dword v141, v[250:251], off offset:-2048
	global_load_dword v142, v[250:251], off offset:-1024
	global_load_dword v143, v[4:5], off offset:-4096
	global_load_dword v144, v[4:5], off offset:-3072
	global_load_dword v145, v[4:5], off offset:-2048
	global_load_dword v146, v[4:5], off offset:-1024
	global_load_dword v147, v[4:5], off
	v_lshl_add_u64 v[4:5], v[4:5], 0, s[8:9]
	global_load_dwordx4 v[152:155], v[6:7], off offset:48
	global_load_dwordx4 v[148:151], v[6:7], off offset:32
	v_add_co_u32_e32 v250, vcc, 0xfffff000, v4
	s_nop 1
	v_addc_co_u32_e32 v251, vcc, -1, v5, vcc
	global_load_dword v156, v[250:251], off offset:-3072
	global_load_dword v157, v[250:251], off offset:-2048
	global_load_dword v158, v[250:251], off offset:-1024
	global_load_dword v159, v[4:5], off offset:-4096
	global_load_dword v160, v[4:5], off offset:-3072
	global_load_dword v161, v[4:5], off offset:-2048
	global_load_dword v162, v[4:5], off offset:-1024
	global_load_dword v163, v[4:5], off
	v_lshl_add_u64 v[4:5], v[4:5], 0, s[8:9]
	global_load_dwordx4 v[184:187], v[6:7], off offset:80
	global_load_dwordx4 v[180:183], v[6:7], off offset:64
	v_add_co_u32_e32 v250, vcc, 0xfffff000, v4
	s_nop 1
	v_addc_co_u32_e32 v251, vcc, -1, v5, vcc
	global_load_dword v188, v[250:251], off offset:-3072
	global_load_dword v189, v[250:251], off offset:-2048
	global_load_dword v190, v[250:251], off offset:-1024
	global_load_dword v191, v[4:5], off offset:-4096
	global_load_dword v192, v[4:5], off offset:-3072
	global_load_dword v193, v[4:5], off offset:-2048
	global_load_dword v194, v[4:5], off offset:-1024
	global_load_dword v195, v[4:5], off
	v_lshl_add_u64 v[4:5], v[4:5], 0, s[8:9]
	global_load_dwordx4 v[216:219], v[6:7], off offset:112
	global_load_dwordx4 v[212:215], v[6:7], off offset:96
	v_add_co_u32_e32 v250, vcc, 0xfffff000, v4
	s_nop 1
	v_addc_co_u32_e32 v251, vcc, -1, v5, vcc
	global_load_dword v220, v[250:251], off offset:-3072
	global_load_dword v221, v[250:251], off offset:-2048
	global_load_dword v222, v[250:251], off offset:-1024
	global_load_dword v223, v[4:5], off offset:-4096
	global_load_dword v224, v[4:5], off offset:-3072
	global_load_dword v225, v[4:5], off offset:-2048
	global_load_dword v226, v[4:5], off offset:-1024
	global_load_dword v227, v[4:5], off
	v_lshl_add_u64 v[4:5], v[4:5], 0, s[8:9]
	global_load_dwordx4 v[232:235], v[6:7], off offset:144
	global_load_dwordx4 v[228:231], v[6:7], off offset:128
	v_add_co_u32_e32 v250, vcc, 0xfffff000, v4
	s_nop 1
	v_addc_co_u32_e32 v251, vcc, -1, v5, vcc
	global_load_dword v236, v[250:251], off offset:-3072
	global_load_dword v237, v[250:251], off offset:-2048
	global_load_dword v238, v[250:251], off offset:-1024
	global_load_dword v239, v[4:5], off offset:-4096
	global_load_dword v240, v[4:5], off offset:-3072
	global_load_dword v241, v[4:5], off offset:-2048
	global_load_dword v242, v[4:5], off offset:-1024
	global_load_dword v243, v[4:5], off
	v_lshl_add_u64 v[4:5], v[4:5], 0, s[8:9]
	s_waitcnt vmcnt(48)
	s_waitcnt vmcnt(47)
	v_fmac_f32_e32 v18, v132, v140
	s_waitcnt vmcnt(46)
	v_fmac_f32_e32 v18, v133, v141
	s_waitcnt vmcnt(45)
	v_fmac_f32_e32 v18, v134, v142
	s_waitcnt vmcnt(44)
	v_fmac_f32_e32 v18, v135, v143
	s_waitcnt vmcnt(43)
	v_fmac_f32_e32 v18, v136, v144
	s_waitcnt vmcnt(42)
	v_fmac_f32_e32 v18, v137, v145
	s_waitcnt vmcnt(41)
	v_fmac_f32_e32 v18, v138, v146
	s_waitcnt vmcnt(40)
	v_fmac_f32_e32 v18, v139, v147
	global_load_dwordx4 v[136:139], v[6:7], off offset:176
	global_load_dwordx4 v[132:135], v[6:7], off offset:160
	v_add_co_u32_e32 v250, vcc, 0xfffff000, v4
	s_nop 1
	v_addc_co_u32_e32 v251, vcc, -1, v5, vcc
	global_load_dword v140, v[250:251], off offset:-3072
	global_load_dword v141, v[250:251], off offset:-2048
	global_load_dword v142, v[250:251], off offset:-1024
	global_load_dword v143, v[4:5], off offset:-4096
	global_load_dword v144, v[4:5], off offset:-3072
	global_load_dword v145, v[4:5], off offset:-2048
	global_load_dword v146, v[4:5], off offset:-1024
	global_load_dword v147, v[4:5], off
	v_lshl_add_u64 v[4:5], v[4:5], 0, s[8:9]
	s_waitcnt vmcnt(48)
	s_waitcnt vmcnt(47)
	v_fmac_f32_e32 v18, v148, v156
	s_waitcnt vmcnt(46)
	v_fmac_f32_e32 v18, v149, v157
	s_waitcnt vmcnt(45)
	v_fmac_f32_e32 v18, v150, v158
	s_waitcnt vmcnt(44)
	v_fmac_f32_e32 v18, v151, v159
	s_waitcnt vmcnt(43)
	v_fmac_f32_e32 v18, v152, v160
	s_waitcnt vmcnt(42)
	v_fmac_f32_e32 v18, v153, v161
	s_waitcnt vmcnt(41)
	v_fmac_f32_e32 v18, v154, v162
	s_waitcnt vmcnt(40)
	v_fmac_f32_e32 v18, v155, v163
	global_load_dwordx4 v[152:155], v[6:7], off offset:208
	global_load_dwordx4 v[148:151], v[6:7], off offset:192
	v_add_co_u32_e32 v250, vcc, 0xfffff000, v4
	s_nop 1
	v_addc_co_u32_e32 v251, vcc, -1, v5, vcc
	global_load_dword v156, v[250:251], off offset:-3072
	global_load_dword v157, v[250:251], off offset:-2048
	global_load_dword v158, v[250:251], off offset:-1024
	global_load_dword v159, v[4:5], off offset:-4096
	global_load_dword v160, v[4:5], off offset:-3072
	global_load_dword v161, v[4:5], off offset:-2048
	global_load_dword v162, v[4:5], off offset:-1024
	global_load_dword v163, v[4:5], off
	v_lshl_add_u64 v[4:5], v[4:5], 0, s[8:9]
	s_waitcnt vmcnt(48)
	s_waitcnt vmcnt(47)
	v_fmac_f32_e32 v18, v180, v188
	s_waitcnt vmcnt(46)
	v_fmac_f32_e32 v18, v181, v189
	s_waitcnt vmcnt(45)
	v_fmac_f32_e32 v18, v182, v190
	s_waitcnt vmcnt(44)
	v_fmac_f32_e32 v18, v183, v191
	s_waitcnt vmcnt(43)
	v_fmac_f32_e32 v18, v184, v192
	s_waitcnt vmcnt(42)
	v_fmac_f32_e32 v18, v185, v193
	s_waitcnt vmcnt(41)
	v_fmac_f32_e32 v18, v186, v194
	s_waitcnt vmcnt(40)
	v_fmac_f32_e32 v18, v187, v195
	global_load_dwordx4 v[184:187], v[6:7], off offset:240
	global_load_dwordx4 v[180:183], v[6:7], off offset:224
	v_add_co_u32_e32 v250, vcc, 0xfffff000, v4
	s_nop 1
	v_addc_co_u32_e32 v251, vcc, -1, v5, vcc
	global_load_dword v188, v[250:251], off offset:-3072
	global_load_dword v189, v[250:251], off offset:-2048
	global_load_dword v190, v[250:251], off offset:-1024
	global_load_dword v191, v[4:5], off offset:-4096
	global_load_dword v192, v[4:5], off offset:-3072
	global_load_dword v193, v[4:5], off offset:-2048
	global_load_dword v194, v[4:5], off offset:-1024
	global_load_dword v195, v[4:5], off
	v_lshl_add_u64 v[4:5], v[4:5], 0, s[8:9]
	s_waitcnt vmcnt(48)
	s_waitcnt vmcnt(47)
	v_fmac_f32_e32 v18, v212, v220
	s_waitcnt vmcnt(46)
	v_fmac_f32_e32 v18, v213, v221
	s_waitcnt vmcnt(45)
	v_fmac_f32_e32 v18, v214, v222
	s_waitcnt vmcnt(44)
	v_fmac_f32_e32 v18, v215, v223
	s_waitcnt vmcnt(43)
	v_fmac_f32_e32 v18, v216, v224
	s_waitcnt vmcnt(42)
	v_fmac_f32_e32 v18, v217, v225
	s_waitcnt vmcnt(41)
	v_fmac_f32_e32 v18, v218, v226
	s_waitcnt vmcnt(40)
	v_fmac_f32_e32 v18, v219, v227
	global_load_dwordx4 v[216:219], v[6:7], off offset:272
	global_load_dwordx4 v[212:215], v[6:7], off offset:256
	v_add_co_u32_e32 v250, vcc, 0xfffff000, v4
	s_nop 1
	v_addc_co_u32_e32 v251, vcc, -1, v5, vcc
	global_load_dword v220, v[250:251], off offset:-3072
	global_load_dword v221, v[250:251], off offset:-2048
	global_load_dword v222, v[250:251], off offset:-1024
	global_load_dword v223, v[4:5], off offset:-4096
	global_load_dword v224, v[4:5], off offset:-3072
	global_load_dword v225, v[4:5], off offset:-2048
	global_load_dword v226, v[4:5], off offset:-1024
	global_load_dword v227, v[4:5], off
	v_lshl_add_u64 v[4:5], v[4:5], 0, s[8:9]
	s_waitcnt vmcnt(48)
	s_waitcnt vmcnt(47)
	v_fmac_f32_e32 v18, v228, v236
	s_waitcnt vmcnt(46)
	v_fmac_f32_e32 v18, v229, v237
	s_waitcnt vmcnt(45)
	v_fmac_f32_e32 v18, v230, v238
	s_waitcnt vmcnt(44)
	v_fmac_f32_e32 v18, v231, v239
	s_waitcnt vmcnt(43)
	v_fmac_f32_e32 v18, v232, v240
	s_waitcnt vmcnt(42)
	v_fmac_f32_e32 v18, v233, v241
	s_waitcnt vmcnt(41)
	v_fmac_f32_e32 v18, v234, v242
	s_waitcnt vmcnt(40)
	v_fmac_f32_e32 v18, v235, v243
	global_load_dwordx4 v[232:235], v[6:7], off offset:304
	global_load_dwordx4 v[228:231], v[6:7], off offset:288
	v_add_co_u32_e32 v250, vcc, 0xfffff000, v4
	s_nop 1
	v_addc_co_u32_e32 v251, vcc, -1, v5, vcc
	global_load_dword v236, v[250:251], off offset:-3072
	global_load_dword v237, v[250:251], off offset:-2048
	global_load_dword v238, v[250:251], off offset:-1024
	global_load_dword v239, v[4:5], off offset:-4096
	global_load_dword v240, v[4:5], off offset:-3072
	global_load_dword v241, v[4:5], off offset:-2048
	global_load_dword v242, v[4:5], off offset:-1024
	global_load_dword v243, v[4:5], off
	v_lshl_add_u64 v[4:5], v[4:5], 0, s[8:9]
	s_waitcnt vmcnt(48)
	s_waitcnt vmcnt(47)
	v_fmac_f32_e32 v18, v132, v140
	s_waitcnt vmcnt(46)
	v_fmac_f32_e32 v18, v133, v141
	s_waitcnt vmcnt(45)
	v_fmac_f32_e32 v18, v134, v142
	s_waitcnt vmcnt(44)
	v_fmac_f32_e32 v18, v135, v143
	s_waitcnt vmcnt(43)
	v_fmac_f32_e32 v18, v136, v144
	s_waitcnt vmcnt(42)
	v_fmac_f32_e32 v18, v137, v145
	s_waitcnt vmcnt(41)
	v_fmac_f32_e32 v18, v138, v146
	s_waitcnt vmcnt(40)
	v_fmac_f32_e32 v18, v139, v147
	global_load_dwordx4 v[136:139], v[6:7], off offset:336
	global_load_dwordx4 v[132:135], v[6:7], off offset:320
	v_add_co_u32_e32 v250, vcc, 0xfffff000, v4
	s_nop 1
	v_addc_co_u32_e32 v251, vcc, -1, v5, vcc
	global_load_dword v140, v[250:251], off offset:-3072
	global_load_dword v141, v[250:251], off offset:-2048
	global_load_dword v142, v[250:251], off offset:-1024
	global_load_dword v143, v[4:5], off offset:-4096
	global_load_dword v144, v[4:5], off offset:-3072
	global_load_dword v145, v[4:5], off offset:-2048
	global_load_dword v146, v[4:5], off offset:-1024
	global_load_dword v147, v[4:5], off
	v_lshl_add_u64 v[4:5], v[4:5], 0, s[8:9]
	s_waitcnt vmcnt(48)
	s_waitcnt vmcnt(47)
	v_fmac_f32_e32 v18, v148, v156
	s_waitcnt vmcnt(46)
	v_fmac_f32_e32 v18, v149, v157
	s_waitcnt vmcnt(45)
	v_fmac_f32_e32 v18, v150, v158
	s_waitcnt vmcnt(44)
	v_fmac_f32_e32 v18, v151, v159
	s_waitcnt vmcnt(43)
	v_fmac_f32_e32 v18, v152, v160
	s_waitcnt vmcnt(42)
	v_fmac_f32_e32 v18, v153, v161
	s_waitcnt vmcnt(41)
	v_fmac_f32_e32 v18, v154, v162
	s_waitcnt vmcnt(40)
	v_fmac_f32_e32 v18, v155, v163
	global_load_dwordx4 v[152:155], v[6:7], off offset:368
	global_load_dwordx4 v[148:151], v[6:7], off offset:352
	v_add_co_u32_e32 v250, vcc, 0xfffff000, v4
	s_nop 1
	v_addc_co_u32_e32 v251, vcc, -1, v5, vcc
	global_load_dword v156, v[250:251], off offset:-3072
	global_load_dword v157, v[250:251], off offset:-2048
	global_load_dword v158, v[250:251], off offset:-1024
	global_load_dword v159, v[4:5], off offset:-4096
	global_load_dword v160, v[4:5], off offset:-3072
	global_load_dword v161, v[4:5], off offset:-2048
	global_load_dword v162, v[4:5], off offset:-1024
	global_load_dword v163, v[4:5], off
	v_lshl_add_u64 v[4:5], v[4:5], 0, s[8:9]
	s_waitcnt vmcnt(48)
	s_waitcnt vmcnt(47)
	v_fmac_f32_e32 v18, v180, v188
	s_waitcnt vmcnt(46)
	v_fmac_f32_e32 v18, v181, v189
	s_waitcnt vmcnt(45)
	v_fmac_f32_e32 v18, v182, v190
	s_waitcnt vmcnt(44)
	v_fmac_f32_e32 v18, v183, v191
	s_waitcnt vmcnt(43)
	v_fmac_f32_e32 v18, v184, v192
	s_waitcnt vmcnt(42)
	v_fmac_f32_e32 v18, v185, v193
	s_waitcnt vmcnt(41)
	v_fmac_f32_e32 v18, v186, v194
	s_waitcnt vmcnt(40)
	v_fmac_f32_e32 v18, v187, v195
	global_load_dwordx4 v[184:187], v[6:7], off offset:400
	global_load_dwordx4 v[180:183], v[6:7], off offset:384
	v_add_co_u32_e32 v250, vcc, 0xfffff000, v4
	s_nop 1
	v_addc_co_u32_e32 v251, vcc, -1, v5, vcc
	global_load_dword v188, v[250:251], off offset:-3072
	global_load_dword v189, v[250:251], off offset:-2048
	global_load_dword v190, v[250:251], off offset:-1024
	global_load_dword v191, v[4:5], off offset:-4096
	global_load_dword v192, v[4:5], off offset:-3072
	global_load_dword v193, v[4:5], off offset:-2048
	global_load_dword v194, v[4:5], off offset:-1024
	global_load_dword v195, v[4:5], off
	v_lshl_add_u64 v[4:5], v[4:5], 0, s[8:9]
	s_waitcnt vmcnt(48)
	s_waitcnt vmcnt(47)
	v_fmac_f32_e32 v18, v212, v220
	s_waitcnt vmcnt(46)
	v_fmac_f32_e32 v18, v213, v221
	s_waitcnt vmcnt(45)
	v_fmac_f32_e32 v18, v214, v222
	s_waitcnt vmcnt(44)
	v_fmac_f32_e32 v18, v215, v223
	s_waitcnt vmcnt(43)
	v_fmac_f32_e32 v18, v216, v224
	s_waitcnt vmcnt(42)
	v_fmac_f32_e32 v18, v217, v225
	s_waitcnt vmcnt(41)
	v_fmac_f32_e32 v18, v218, v226
	s_waitcnt vmcnt(40)
	v_fmac_f32_e32 v18, v219, v227
	global_load_dwordx4 v[216:219], v[6:7], off offset:432
	global_load_dwordx4 v[212:215], v[6:7], off offset:416
	v_add_co_u32_e32 v250, vcc, 0xfffff000, v4
	s_nop 1
	v_addc_co_u32_e32 v251, vcc, -1, v5, vcc
	global_load_dword v220, v[250:251], off offset:-3072
	global_load_dword v221, v[250:251], off offset:-2048
	global_load_dword v222, v[250:251], off offset:-1024
	global_load_dword v223, v[4:5], off offset:-4096
	global_load_dword v224, v[4:5], off offset:-3072
	global_load_dword v225, v[4:5], off offset:-2048
	global_load_dword v226, v[4:5], off offset:-1024
	global_load_dword v227, v[4:5], off
	v_lshl_add_u64 v[4:5], v[4:5], 0, s[8:9]
	s_waitcnt vmcnt(48)
	s_waitcnt vmcnt(47)
	v_fmac_f32_e32 v18, v228, v236
	s_waitcnt vmcnt(46)
	v_fmac_f32_e32 v18, v229, v237
	s_waitcnt vmcnt(45)
	v_fmac_f32_e32 v18, v230, v238
	s_waitcnt vmcnt(44)
	v_fmac_f32_e32 v18, v231, v239
	s_waitcnt vmcnt(43)
	v_fmac_f32_e32 v18, v232, v240
	s_waitcnt vmcnt(42)
	v_fmac_f32_e32 v18, v233, v241
	s_waitcnt vmcnt(41)
	v_fmac_f32_e32 v18, v234, v242
	s_waitcnt vmcnt(40)
	v_fmac_f32_e32 v18, v235, v243
	global_load_dwordx4 v[232:235], v[6:7], off offset:464
	global_load_dwordx4 v[228:231], v[6:7], off offset:448
	v_add_co_u32_e32 v250, vcc, 0xfffff000, v4
	s_nop 1
	v_addc_co_u32_e32 v251, vcc, -1, v5, vcc
	global_load_dword v236, v[250:251], off offset:-3072
	global_load_dword v237, v[250:251], off offset:-2048
	global_load_dword v238, v[250:251], off offset:-1024
	global_load_dword v239, v[4:5], off offset:-4096
	global_load_dword v240, v[4:5], off offset:-3072
	global_load_dword v241, v[4:5], off offset:-2048
	global_load_dword v242, v[4:5], off offset:-1024
	global_load_dword v243, v[4:5], off
	v_lshl_add_u64 v[4:5], v[4:5], 0, s[8:9]
	s_waitcnt vmcnt(48)
	s_waitcnt vmcnt(47)
	v_fmac_f32_e32 v18, v132, v140
	s_waitcnt vmcnt(46)
	v_fmac_f32_e32 v18, v133, v141
	s_waitcnt vmcnt(45)
	v_fmac_f32_e32 v18, v134, v142
	s_waitcnt vmcnt(44)
	v_fmac_f32_e32 v18, v135, v143
	s_waitcnt vmcnt(43)
	v_fmac_f32_e32 v18, v136, v144
	s_waitcnt vmcnt(42)
	v_fmac_f32_e32 v18, v137, v145
	s_waitcnt vmcnt(41)
	v_fmac_f32_e32 v18, v138, v146
	s_waitcnt vmcnt(40)
	v_fmac_f32_e32 v18, v139, v147
	global_load_dwordx4 v[136:139], v[6:7], off offset:496
	global_load_dwordx4 v[132:135], v[6:7], off offset:480
	v_add_co_u32_e32 v250, vcc, 0xfffff000, v4
	s_nop 1
	v_addc_co_u32_e32 v251, vcc, -1, v5, vcc
	global_load_dword v140, v[250:251], off offset:-3072
	global_load_dword v141, v[250:251], off offset:-2048
	global_load_dword v142, v[250:251], off offset:-1024
	global_load_dword v143, v[4:5], off offset:-4096
	global_load_dword v144, v[4:5], off offset:-3072
	global_load_dword v145, v[4:5], off offset:-2048
	global_load_dword v146, v[4:5], off offset:-1024
	global_load_dword v147, v[4:5], off
	v_lshl_add_u64 v[4:5], v[4:5], 0, s[8:9]
	s_waitcnt vmcnt(48)
	s_waitcnt vmcnt(47)
	v_fmac_f32_e32 v18, v148, v156
	s_waitcnt vmcnt(46)
	v_fmac_f32_e32 v18, v149, v157
	s_waitcnt vmcnt(45)
	v_fmac_f32_e32 v18, v150, v158
	s_waitcnt vmcnt(44)
	v_fmac_f32_e32 v18, v151, v159
	s_waitcnt vmcnt(43)
	v_fmac_f32_e32 v18, v152, v160
	s_waitcnt vmcnt(42)
	v_fmac_f32_e32 v18, v153, v161
	s_waitcnt vmcnt(41)
	v_fmac_f32_e32 v18, v154, v162
	s_waitcnt vmcnt(40)
	v_fmac_f32_e32 v18, v155, v163
	s_waitcnt vmcnt(38)
	s_waitcnt vmcnt(37)
	v_fmac_f32_e32 v18, v180, v188
	s_waitcnt vmcnt(36)
	v_fmac_f32_e32 v18, v181, v189
	s_waitcnt vmcnt(35)
	v_fmac_f32_e32 v18, v182, v190
	s_waitcnt vmcnt(34)
	v_fmac_f32_e32 v18, v183, v191
	s_waitcnt vmcnt(33)
	v_fmac_f32_e32 v18, v184, v192
	s_waitcnt vmcnt(32)
	v_fmac_f32_e32 v18, v185, v193
	s_waitcnt vmcnt(31)
	v_fmac_f32_e32 v18, v186, v194
	s_waitcnt vmcnt(30)
	v_fmac_f32_e32 v18, v187, v195
	s_waitcnt vmcnt(28)
	s_waitcnt vmcnt(27)
	v_fmac_f32_e32 v18, v212, v220
	s_waitcnt vmcnt(26)
	v_fmac_f32_e32 v18, v213, v221
	s_waitcnt vmcnt(25)
	v_fmac_f32_e32 v18, v214, v222
	s_waitcnt vmcnt(24)
	v_fmac_f32_e32 v18, v215, v223
	s_waitcnt vmcnt(23)
	v_fmac_f32_e32 v18, v216, v224
	s_waitcnt vmcnt(22)
	v_fmac_f32_e32 v18, v217, v225
	s_waitcnt vmcnt(21)
	v_fmac_f32_e32 v18, v218, v226
	s_waitcnt vmcnt(20)
	v_fmac_f32_e32 v18, v219, v227
	s_waitcnt vmcnt(18)
	s_waitcnt vmcnt(17)
	v_fmac_f32_e32 v18, v228, v236
	s_waitcnt vmcnt(16)
	v_fmac_f32_e32 v18, v229, v237
	s_waitcnt vmcnt(15)
	v_fmac_f32_e32 v18, v230, v238
	s_waitcnt vmcnt(14)
	v_fmac_f32_e32 v18, v231, v239
	s_waitcnt vmcnt(13)
	v_fmac_f32_e32 v18, v232, v240
	s_waitcnt vmcnt(12)
	v_fmac_f32_e32 v18, v233, v241
	s_waitcnt vmcnt(11)
	v_fmac_f32_e32 v18, v234, v242
	s_waitcnt vmcnt(10)
	v_fmac_f32_e32 v18, v235, v243
	s_waitcnt vmcnt(8)
	s_waitcnt vmcnt(7)
	v_fmac_f32_e32 v18, v132, v140
	s_waitcnt vmcnt(6)
	v_fmac_f32_e32 v18, v133, v141
	s_waitcnt vmcnt(5)
	v_fmac_f32_e32 v18, v134, v142
	s_waitcnt vmcnt(4)
	v_fmac_f32_e32 v18, v135, v143
	s_waitcnt vmcnt(3)
	v_fmac_f32_e32 v18, v136, v144
	s_waitcnt vmcnt(2)
	v_fmac_f32_e32 v18, v137, v145
	s_waitcnt vmcnt(1)
	v_fmac_f32_e32 v18, v138, v146
	s_waitcnt vmcnt(0)
	v_fmac_f32_e32 v18, v139, v147
	v_and_b32_e32 v4, 31, v67
	v_lshrrev_b32_e32 v6, 2, v67
	v_lshlrev_b32_e32 v5, 1, v67
	v_and_or_b32 v4, v6, s18, v4
	v_and_b32_e32 v5, 0xc0, v5
	v_lshlrev_b32_e32 v4, 8, v4
	v_or3_b32 v4, v4, v5, v1
	v_add_u32_e32 v67, s72, v67
	v_ashrrev_i32_e32 v5, 31, v4
	v_cmp_lt_i32_e32 vcc, s19, v67
	v_lshl_add_u64 v[4:5], v[4:5], 2, s[4:5]
	v_add_u16_e32 v8, s16, v8
	s_or_b64 s[6:7], vcc, s[6:7]
	v_add_u32_e32 v9, s17, v9
	global_store_dword v[4:5], v18, off
	s_andn2_b64 exec, exec, s[6:7]
	s_cbranch_execnz .LBB0_185

.LBB0_779:
	v_add_f32_e32 v0, 1.0, v183
	v_div_scale_f32 v2, s[4:5], v0, v0, 1.0
	v_rcp_f32_e32 v3, v2
	s_mov_b64 s[40:41], 0
	s_waitcnt vmcnt(7)
	v_fma_f32 v8, -v2, v3, 1.0
	v_fmac_f32_e32 v3, v8, v3
	v_div_scale_f32 v8, vcc, 1.0, v0, 1.0
	v_mul_f32_e32 v9, v8, v3
	v_fma_f32 v10, -v2, v9, v8
	v_fmac_f32_e32 v9, v10, v3
	v_fma_f32 v2, -v2, v9, v8
	v_div_fmas_f32 v2, v2, v3, v9
	v_div_fixup_f32 v0, v2, v0, 1.0
	v_add_f32_e32 v2, 1.0, v177
	v_div_scale_f32 v3, s[4:5], v2, v2, 1.0
	v_rcp_f32_e32 v8, v3
	v_mov_b32_e32 v177, v1
	v_fma_f32 v9, -v3, v8, 1.0
	v_fmac_f32_e32 v8, v9, v8
	v_div_scale_f32 v9, vcc, 1.0, v2, 1.0
	v_mul_f32_e32 v10, v9, v8
	v_fma_f32 v11, -v3, v10, v9
	v_fmac_f32_e32 v10, v11, v8
	v_fma_f32 v3, -v3, v10, v9
	v_div_fmas_f32 v3, v3, v8, v10
	v_div_scale_f32 v8, s[4:5], v85, v85, v0
	v_rcp_f32_e32 v9, v8
	v_div_fixup_f32 v10, v3, v2, 1.0
	v_lshl_add_u64 v[2:3], v[176:177], 1, s[2:3]
	v_fma_f32 v11, -v8, v9, 1.0
	v_fmac_f32_e32 v9, v11, v9
	v_div_scale_f32 v11, vcc, v0, v85, v0
	s_waitcnt vmcnt(6)
	v_mul_f32_e32 v12, v11, v9
	v_fma_f32 v13, -v8, v12, v11
	v_fmac_f32_e32 v12, v13, v9
	v_fma_f32 v8, -v8, v12, v11
	v_div_fmas_f32 v8, v8, v9, v12
	v_div_fixup_f32 v0, v8, v85, v0
	v_lshl_add_u64 v[8:9], v[166:167], 1, v[2:3]
	v_lshl_add_u64 v[146:147], v[170:171], 1, v[2:3]
	global_load_dwordx2 v[18:19], v[8:9], off sc1
	global_load_dwordx2 v[20:21], v[8:9], off offset:32 sc1
	global_load_dwordx2 v[22:23], v[8:9], off offset:64 sc1
	global_load_dwordx2 v[26:27], v[8:9], off offset:96 sc1
	global_load_dwordx2 v[28:29], v[8:9], off offset:128 sc1
	global_load_dwordx2 v[30:31], v[8:9], off offset:160 sc1
	global_load_dwordx2 v[32:33], v[8:9], off offset:192 sc1
	global_load_dwordx2 v[36:37], v[8:9], off offset:224 sc1
	global_load_dwordx2 v[38:39], v[146:147], off sc1
	global_load_dwordx2 v[132:133], v[146:147], off offset:32 sc1
	global_load_dwordx2 v[134:135], v[146:147], off offset:64 sc1
	global_load_dwordx2 v[136:137], v[146:147], off offset:96 sc1
	global_load_dwordx2 v[138:139], v[146:147], off offset:128 sc1
	global_load_dwordx2 v[140:141], v[146:147], off offset:160 sc1
	global_load_dwordx2 v[142:143], v[146:147], off offset:192 sc1
	global_load_dwordx2 v[144:145], v[146:147], off offset:224 sc1
	s_waitcnt vmcnt(15)
	v_mov_b32_e32 v16, v18
	v_mov_b32_e32 v17, v19
	v_pk_mul_f32 v[14:15], v[112:113], v[0:1] op_sel_hi:[1,0]
	v_pk_mul_f32 v[12:13], v[114:115], v[0:1] op_sel_hi:[1,0]
	v_lshl_add_u64 v[2:3], v[170:171], 1, v[2:3]
	s_nop 0
	v_lshlrev_b32_e32 v11, 16, v16
	v_add_f32_e32 v11, v14, v11
	v_and_b32_e32 v14, 0xffff0000, v16
	v_add_f32_e32 v14, v15, v14
	v_lshlrev_b32_e32 v15, 16, v17
	v_add_f32_e32 v15, v12, v15
	v_and_b32_e32 v12, 0xffff0000, v17
	v_add_f32_e32 v13, v13, v12
	v_cvt_pk_bf16_f32 v12, v11, v14
	v_cvt_pk_bf16_f32 v13, v15, v13
	global_store_dwordx2 v[8:9], v[12:13], off
	s_waitcnt vmcnt(15)
	v_mov_b32_e32 v16, v20
	v_mov_b32_e32 v17, v21
	v_pk_mul_f32 v[14:15], v[108:109], v[0:1] op_sel_hi:[1,0]
	v_pk_mul_f32 v[12:13], v[110:111], v[0:1] op_sel_hi:[1,0]
	s_nop 0
	v_lshlrev_b32_e32 v11, 16, v16
	v_add_f32_e32 v11, v14, v11
	v_and_b32_e32 v14, 0xffff0000, v16
	v_add_f32_e32 v14, v15, v14
	v_lshlrev_b32_e32 v15, 16, v17
	v_add_f32_e32 v15, v12, v15
	v_and_b32_e32 v12, 0xffff0000, v17
	v_add_f32_e32 v13, v13, v12
	v_cvt_pk_bf16_f32 v12, v11, v14
	v_cvt_pk_bf16_f32 v13, v15, v13
	global_store_dwordx2 v[8:9], v[12:13], off offset:32
	s_waitcnt vmcnt(15)
	v_mov_b32_e32 v16, v22
	v_mov_b32_e32 v17, v23
	v_pk_mul_f32 v[14:15], v[104:105], v[0:1] op_sel_hi:[1,0]
	v_pk_mul_f32 v[12:13], v[106:107], v[0:1] op_sel_hi:[1,0]
	s_nop 0
	v_lshlrev_b32_e32 v11, 16, v16
	v_add_f32_e32 v11, v14, v11
	v_and_b32_e32 v14, 0xffff0000, v16
	v_add_f32_e32 v14, v15, v14
	v_lshlrev_b32_e32 v15, 16, v17
	v_add_f32_e32 v15, v12, v15
	v_and_b32_e32 v12, 0xffff0000, v17
	v_add_f32_e32 v13, v13, v12
	v_cvt_pk_bf16_f32 v12, v11, v14
	v_cvt_pk_bf16_f32 v13, v15, v13
	global_store_dwordx2 v[8:9], v[12:13], off offset:64
	s_waitcnt vmcnt(15)
	v_mov_b32_e32 v16, v26
	v_mov_b32_e32 v17, v27
	v_pk_mul_f32 v[14:15], v[100:101], v[0:1] op_sel_hi:[1,0]
	v_pk_mul_f32 v[12:13], v[102:103], v[0:1] op_sel_hi:[1,0]
	s_nop 0
	v_lshlrev_b32_e32 v11, 16, v16
	v_add_f32_e32 v11, v14, v11
	v_and_b32_e32 v14, 0xffff0000, v16
	v_add_f32_e32 v14, v15, v14
	v_lshlrev_b32_e32 v15, 16, v17
	v_add_f32_e32 v15, v12, v15
	v_and_b32_e32 v12, 0xffff0000, v17
	v_add_f32_e32 v13, v13, v12
	v_cvt_pk_bf16_f32 v12, v11, v14
	v_cvt_pk_bf16_f32 v13, v15, v13
	global_store_dwordx2 v[8:9], v[12:13], off offset:96
	s_waitcnt vmcnt(15)
	v_mov_b32_e32 v16, v28
	v_mov_b32_e32 v17, v29
	v_pk_mul_f32 v[14:15], v[80:81], v[0:1] op_sel_hi:[1,0]
	v_pk_mul_f32 v[12:13], v[82:83], v[0:1] op_sel_hi:[1,0]
	s_nop 0
	v_lshlrev_b32_e32 v11, 16, v16
	v_add_f32_e32 v11, v14, v11
	v_and_b32_e32 v14, 0xffff0000, v16
	v_add_f32_e32 v14, v15, v14
	v_lshlrev_b32_e32 v15, 16, v17
	v_add_f32_e32 v15, v12, v15
	v_and_b32_e32 v12, 0xffff0000, v17
	v_add_f32_e32 v13, v13, v12
	v_cvt_pk_bf16_f32 v12, v11, v14
	v_cvt_pk_bf16_f32 v13, v15, v13
	global_store_dwordx2 v[8:9], v[12:13], off offset:128
	s_waitcnt vmcnt(15)
	v_mov_b32_e32 v16, v30
	v_mov_b32_e32 v17, v31
	v_pk_mul_f32 v[14:15], v[76:77], v[0:1] op_sel_hi:[1,0]
	v_pk_mul_f32 v[12:13], v[78:79], v[0:1] op_sel_hi:[1,0]
	s_nop 0
	v_lshlrev_b32_e32 v11, 16, v16
	v_add_f32_e32 v11, v14, v11
	v_and_b32_e32 v14, 0xffff0000, v16
	v_add_f32_e32 v14, v15, v14
	v_lshlrev_b32_e32 v15, 16, v17
	v_add_f32_e32 v15, v12, v15
	v_and_b32_e32 v12, 0xffff0000, v17
	v_add_f32_e32 v13, v13, v12
	v_cvt_pk_bf16_f32 v12, v11, v14
	v_cvt_pk_bf16_f32 v13, v15, v13
	global_store_dwordx2 v[8:9], v[12:13], off offset:160
	s_waitcnt vmcnt(15)
	v_mov_b32_e32 v16, v32
	v_mov_b32_e32 v17, v33
	v_pk_mul_f32 v[14:15], v[72:73], v[0:1] op_sel_hi:[1,0]
	v_pk_mul_f32 v[12:13], v[74:75], v[0:1] op_sel_hi:[1,0]
	s_nop 0
	v_lshlrev_b32_e32 v11, 16, v16
	v_add_f32_e32 v11, v14, v11
	v_and_b32_e32 v14, 0xffff0000, v16
	v_add_f32_e32 v14, v15, v14
	v_lshlrev_b32_e32 v15, 16, v17
	v_add_f32_e32 v15, v12, v15
	v_and_b32_e32 v12, 0xffff0000, v17
	v_add_f32_e32 v13, v13, v12
	v_cvt_pk_bf16_f32 v12, v11, v14
	v_cvt_pk_bf16_f32 v13, v15, v13
	global_store_dwordx2 v[8:9], v[12:13], off offset:192
	s_waitcnt vmcnt(15)
	v_mov_b32_e32 v16, v36
	v_mov_b32_e32 v17, v37
	v_pk_mul_f32 v[12:13], v[70:71], v[0:1] op_sel_hi:[1,0]
	v_pk_mul_f32 v[14:15], v[68:69], v[0:1] op_sel_hi:[1,0]
	s_nop 0
	v_lshlrev_b32_e32 v0, 16, v16
	v_add_f32_e32 v0, v14, v0
	v_lshlrev_b32_e32 v14, 16, v17
	v_and_b32_e32 v11, 0xffff0000, v16
	v_add_f32_e32 v14, v12, v14
	v_and_b32_e32 v12, 0xffff0000, v17
	v_add_f32_e32 v11, v15, v11
	v_add_f32_e32 v13, v13, v12
	v_cvt_pk_bf16_f32 v12, v0, v11
	v_div_scale_f32 v0, s[4:5], v84, v84, v10
	v_cvt_pk_bf16_f32 v13, v14, v13
	global_store_dwordx2 v[8:9], v[12:13], off offset:224
	v_rcp_f32_e32 v8, v0
	s_mov_b64 s[4:5], 1
	v_fma_f32 v9, -v0, v8, 1.0
	v_fmac_f32_e32 v8, v9, v8
	v_div_scale_f32 v9, vcc, v10, v84, v10
	v_mul_f32_e32 v11, v9, v8
	v_fma_f32 v12, -v0, v11, v9
	v_fmac_f32_e32 v11, v12, v8
	s_waitcnt vmcnt(15)
	v_mov_b32_e32 v12, v38
	v_mov_b32_e32 v13, v39
	v_fma_f32 v0, -v0, v11, v9
	v_div_fmas_f32 v0, v0, v8, v11
	v_div_fixup_f32 v0, v0, v84, v10
	v_pk_mul_f32 v[10:11], v[64:65], v[0:1] op_sel_hi:[1,0]
	v_pk_mul_f32 v[8:9], v[66:67], v[0:1] op_sel_hi:[1,0]
	v_pk_mul_f32 v[6:7], v[6:7], v[0:1] op_sel_hi:[1,0]
	v_pk_mul_f32 v[4:5], v[4:5], v[0:1] op_sel_hi:[1,0]
	s_andn2_b64 vcc, exec, s[76:77]
	s_nop 0
	v_lshlrev_b32_e32 v14, 16, v12
	v_and_b32_e32 v12, 0xffff0000, v12
	v_add_f32_e32 v11, v11, v12
	v_lshlrev_b32_e32 v12, 16, v13
	v_add_f32_e32 v12, v8, v12
	v_and_b32_e32 v8, 0xffff0000, v13
	v_add_f32_e32 v9, v9, v8
	v_add_f32_e32 v10, v10, v14
	v_cvt_pk_bf16_f32 v8, v10, v11
	v_cvt_pk_bf16_f32 v9, v12, v9
	global_store_dwordx2 v[2:3], v[8:9], off
	s_waitcnt vmcnt(15)
	v_mov_b32_e32 v12, v132
	v_mov_b32_e32 v13, v133
	v_pk_mul_f32 v[10:11], v[60:61], v[0:1] op_sel_hi:[1,0]
	v_pk_mul_f32 v[8:9], v[62:63], v[0:1] op_sel_hi:[1,0]
	s_nop 0
	v_lshlrev_b32_e32 v14, 16, v12
	v_and_b32_e32 v12, 0xffff0000, v12
	v_add_f32_e32 v11, v11, v12
	v_lshlrev_b32_e32 v12, 16, v13
	v_add_f32_e32 v12, v8, v12
	v_and_b32_e32 v8, 0xffff0000, v13
	v_add_f32_e32 v9, v9, v8
	v_add_f32_e32 v10, v10, v14
	v_cvt_pk_bf16_f32 v8, v10, v11
	v_cvt_pk_bf16_f32 v9, v12, v9
	global_store_dwordx2 v[2:3], v[8:9], off offset:32
	s_waitcnt vmcnt(15)
	v_mov_b32_e32 v12, v134
	v_mov_b32_e32 v13, v135
	v_pk_mul_f32 v[10:11], v[56:57], v[0:1] op_sel_hi:[1,0]
	v_pk_mul_f32 v[8:9], v[58:59], v[0:1] op_sel_hi:[1,0]
	s_nop 0
	v_lshlrev_b32_e32 v14, 16, v12
	v_and_b32_e32 v12, 0xffff0000, v12
	v_add_f32_e32 v11, v11, v12
	v_lshlrev_b32_e32 v12, 16, v13
	v_add_f32_e32 v12, v8, v12
	v_and_b32_e32 v8, 0xffff0000, v13
	v_add_f32_e32 v9, v9, v8
	v_add_f32_e32 v10, v10, v14
	v_cvt_pk_bf16_f32 v8, v10, v11
	v_cvt_pk_bf16_f32 v9, v12, v9
	global_store_dwordx2 v[2:3], v[8:9], off offset:64
	s_waitcnt vmcnt(15)
	v_mov_b32_e32 v12, v136
	v_mov_b32_e32 v13, v137
	v_pk_mul_f32 v[10:11], v[52:53], v[0:1] op_sel_hi:[1,0]
	v_pk_mul_f32 v[8:9], v[54:55], v[0:1] op_sel_hi:[1,0]
	s_nop 0
	v_lshlrev_b32_e32 v14, 16, v12
	v_and_b32_e32 v12, 0xffff0000, v12
	v_add_f32_e32 v11, v11, v12
	v_lshlrev_b32_e32 v12, 16, v13
	v_add_f32_e32 v12, v8, v12
	v_and_b32_e32 v8, 0xffff0000, v13
	v_add_f32_e32 v9, v9, v8
	v_add_f32_e32 v10, v10, v14
	v_cvt_pk_bf16_f32 v8, v10, v11
	v_cvt_pk_bf16_f32 v9, v12, v9
	global_store_dwordx2 v[2:3], v[8:9], off offset:96
	s_waitcnt vmcnt(15)
	v_mov_b32_e32 v12, v138
	v_mov_b32_e32 v13, v139
	v_pk_mul_f32 v[10:11], v[48:49], v[0:1] op_sel_hi:[1,0]
	v_pk_mul_f32 v[8:9], v[50:51], v[0:1] op_sel_hi:[1,0]
	s_nop 0
	v_lshlrev_b32_e32 v14, 16, v12
	v_and_b32_e32 v12, 0xffff0000, v12
	v_add_f32_e32 v11, v11, v12
	v_lshlrev_b32_e32 v12, 16, v13
	v_add_f32_e32 v12, v8, v12
	v_and_b32_e32 v8, 0xffff0000, v13
	v_add_f32_e32 v9, v9, v8
	v_add_f32_e32 v10, v10, v14
	v_cvt_pk_bf16_f32 v8, v10, v11
	v_cvt_pk_bf16_f32 v9, v12, v9
	global_store_dwordx2 v[2:3], v[8:9], off offset:128
	s_waitcnt vmcnt(15)
	v_mov_b32_e32 v12, v140
	v_mov_b32_e32 v13, v141
	v_pk_mul_f32 v[10:11], v[44:45], v[0:1] op_sel_hi:[1,0]
	v_pk_mul_f32 v[8:9], v[46:47], v[0:1] op_sel_hi:[1,0]
	s_nop 0
	v_lshlrev_b32_e32 v14, 16, v12
	v_and_b32_e32 v12, 0xffff0000, v12
	v_add_f32_e32 v11, v11, v12
	v_lshlrev_b32_e32 v12, 16, v13
	v_add_f32_e32 v12, v8, v12
	v_and_b32_e32 v8, 0xffff0000, v13
	v_add_f32_e32 v9, v9, v8
	v_add_f32_e32 v10, v10, v14
	v_cvt_pk_bf16_f32 v8, v10, v11
	v_cvt_pk_bf16_f32 v9, v12, v9
	global_store_dwordx2 v[2:3], v[8:9], off offset:160
	s_waitcnt vmcnt(15)
	v_mov_b32_e32 v12, v142
	v_mov_b32_e32 v13, v143
	v_pk_mul_f32 v[10:11], v[40:41], v[0:1] op_sel_hi:[1,0]
	v_pk_mul_f32 v[8:9], v[42:43], v[0:1] op_sel_hi:[1,0]
	s_nop 0
	v_lshlrev_b32_e32 v14, 16, v12
	v_and_b32_e32 v12, 0xffff0000, v12
	v_add_f32_e32 v11, v11, v12
	v_lshlrev_b32_e32 v12, 16, v13
	v_add_f32_e32 v12, v8, v12
	v_and_b32_e32 v8, 0xffff0000, v13
	v_add_f32_e32 v9, v9, v8
	v_add_f32_e32 v10, v10, v14
	v_cvt_pk_bf16_f32 v8, v10, v11
	v_cvt_pk_bf16_f32 v9, v12, v9
	global_store_dwordx2 v[2:3], v[8:9], off offset:192
	s_waitcnt vmcnt(15)
	v_mov_b32_e32 v8, v144
	v_mov_b32_e32 v9, v145
	s_nop 0
	v_lshlrev_b32_e32 v0, 16, v8
	v_add_f32_e32 v0, v4, v0
	v_and_b32_e32 v4, 0xffff0000, v8
	v_add_f32_e32 v4, v5, v4
	v_lshlrev_b32_e32 v5, 16, v9
	v_add_f32_e32 v5, v6, v5
	v_and_b32_e32 v6, 0xffff0000, v9
	v_add_f32_e32 v6, v7, v6
	v_cvt_pk_bf16_f32 v4, v0, v4
	v_cvt_pk_bf16_f32 v5, v5, v6
	global_store_dwordx2 v[2:3], v[4:5], off offset:224
	s_cbranch_vccz .LBB0_770
